# same as previous group-barrier version with the XCC-consistency predicate hardened (published id+1 must be nonzero)
# speedup vs baseline: 1.0016x; 1.0016x over previous
_Z4mega6Params:
	s_mov_b32 s32, 0
	s_load_dwordx8 s[20:27], s[0:1], 0x120
	s_load_dwordx8 s[4:11], s[0:1], 0x100
	s_load_dword s97, s[0:1], 0x140
	v_and_b32_e32 v144, 0x3ff, v0
	s_mov_b32 s3, s2
	v_cmp_gt_u32_e64 s[18:19], 4, v144
	s_waitcnt lgkmcnt(0)
	v_writelane_b32 v248, s4, 0
	s_nop 1
	v_writelane_b32 v248, s5, 1
	v_writelane_b32 v248, s6, 2
	v_writelane_b32 v248, s7, 3
	v_writelane_b32 v248, s8, 4
	v_writelane_b32 v248, s9, 5
	v_writelane_b32 v248, s10, 6
	v_writelane_b32 v248, s11, 7
	s_add_u32 s8, s0, 0x138
	s_addc_u32 s9, s1, 0
	s_and_saveexec_b64 s[4:5], s[18:19]
	v_lshl_add_u32 v1, v144, 2, 0
	v_add_u32_e32 v1, 0x23fe0, v1
	v_mov_b32_e32 v2, 0
	ds_write_b32 v1, v2
	s_or_b64 exec, exec, s[4:5]
	s_waitcnt lgkmcnt(0)
	s_barrier
	s_add_u32 s94, s22, 0x1be4c100
	s_getreg_b32 s2, hwreg(HW_REG_XCC_ID, 0, 4)
	s_addc_u32 s95, s23, 0
	s_and_b32 s96, s2, 15
	v_cmp_eq_u32_e64 s[4:5], 0, v144
	s_and_saveexec_b64 s[6:7], s[4:5]
	s_cbranch_execz .LBB0_5
	s_mov_b64 s[10:11], exec
	v_mbcnt_lo_u32_b32 v1, s10, 0
	v_mbcnt_hi_u32_b32 v1, s11, v1
	v_cmp_eq_u32_e32 vcc, 0, v1
	s_and_b64 s[12:13], exec, vcc
	s_mov_b64 exec, s[12:13]
	s_cbranch_execz .LBB0_5
	s_lshl_b32 s2, s96, 8
	s_bcnt1_i32_b64 s10, s[10:11]
	v_mov_b32_e32 v1, s2
	v_mov_b32_e32 v2, s10
	global_atomic_add v1, v2, s[94:95] offset:1024
	v_mov_b32_e32 v3, s3
	v_mov_b32_e32 v4, s96
	v_add_u32_e32 v4, 1, v4
	global_store_byte v3, v4, s[94:95]

.LBB0_914:
	s_cmp_lt_i32 s24, 5
	s_cselect_b64 s[6:7], -1, 0
	s_and_b64 s[0:1], s[6:7], s[0:1]
	s_andn2_b64 vcc, exec, s[0:1]
	s_cbranch_vccnz .LBB0_943
	s_add_u32 s8, s22, 0x1be4c100
	s_addc_u32 s9, s23, 0
	v_and_b32_e32 v0, 63, v144
	global_load_ubyte v1, v0, s[8:9] sc1
	global_load_ubyte v2, v0, s[8:9] offset:64 sc1
	global_load_ubyte v3, v0, s[8:9] offset:128 sc1
	global_load_ubyte v4, v0, s[8:9] offset:192 sc1
	s_waitcnt vmcnt(0)
	v_cmp_eq_u32_e32 vcc, v1, v2
	v_cmp_eq_u32_e64 s[10:11], v1, v3
	v_cmp_eq_u32_e64 s[12:13], v1, v4
	v_cmp_ne_u32_e64 s[14:15], 0, v1
	s_nop 3
	s_and_b64 s[10:11], s[10:11], s[12:13]
	s_and_b64 s[10:11], s[10:11], s[14:15]
	s_and_b64 vcc, vcc, s[10:11]
	s_cmp_eq_u64 vcc, exec
	s_cselect_b32 s32, 1, 0
	s_cmp_eq_u32 s32, 0
	s_cbranch_scc1 .Lstag_done
	s_and_b32 s98, s3, 3
	s_cmp_eq_u32 s98, 0
	s_cbranch_scc1 .Lstag_done
